# residual epilogue: the two f32 stores that complete one 128-byte line are issued back-to-back
# speedup vs baseline: 1.0069x; 1.0037x over previous
.LBB0_874:
	s_cmpk_gt_i32 s56, 0x7f
	s_cbranch_scc1 .Lresid_orig
	s_and_b64 vcc, exec, s[10:11]
	s_cbranch_vccz .Lresid_nonorm
	v_readlane_b32 s62, v252, 7
	v_readlane_b32 s63, v252, 8
	s_lshr_b32 s20, s56, 4
	s_mul_i32 s20, s20, 0x6000
	s_add_u32 s44, s66, s20
	s_addc_u32 s45, s12, 0
	s_add_u32 s46, s13, s20
	s_addc_u32 s47, s26, 0
	s_mov_b32 s60, s38
	s_mov_b32 s61, s95
	v_lshl_or_b32 v236, s57, 8, v246
	v_lshl_add_u32 v237, s56, 8, v244
	v_lshlrev_b32_e32 v210, 2, v236
	v_lshl_add_u32 v211, v237, 12, v210
	v_and_b32_e32 v212, 4, v246
	v_mul_u32_u24_e32 v212, 6, v212
	v_lshl_add_u32 v212, v236, 1, v212
	v_lshl_add_u32 v212, v237, 11, v212
	v_lshlrev_b32_e32 v213, 2, v237
	v_lshlrev_b32_e32 v214, 2, v231
	v_lshlrev_b32_e32 v215, 2, v232
	global_load_dwordx4 v[60:63], v210, s[44:45] offset:0
	global_load_dwordx4 v[64:67], v210, s[44:45] offset:64
	global_load_dwordx4 v[68:71], v210, s[44:45] offset:512
	global_load_dwordx4 v[72:75], v210, s[44:45] offset:576
	global_load_dwordx4 v[148:151], v210, s[46:47] offset:0
	global_load_dwordx4 v[152:155], v210, s[46:47] offset:64
	global_load_dwordx4 v[156:159], v210, s[46:47] offset:512
	global_load_dwordx4 v[160:163], v210, s[46:47] offset:576
	global_load_dwordx4 v[194:197], v210, s[8:9] offset:0
	global_load_dwordx4 v[198:201], v210, s[8:9] offset:64
	global_load_dwordx4 v[202:205], v210, s[8:9] offset:512
	global_load_dwordx4 v[206:209], v210, s[8:9] offset:576
	s_mov_b32 s72, s60
	s_mov_b32 s73, s61
	global_load_dwordx4 v[164:167], v211, s[72:73] offset:0
	global_load_dwordx4 v[168:171], v211, s[72:73] offset:64
	global_load_dwordx4 v[172:175], v211, s[72:73] offset:512
	global_load_dwordx4 v[176:179], v211, s[72:73] offset:576
	s_waitcnt vmcnt(4)
	v_pk_add_f32 v[148:149], v[148:149], 1.0 op_sel_hi:[1,0]
	v_pk_add_f32 v[150:151], v[150:151], 1.0 op_sel_hi:[1,0]
	v_pk_mul_f32 v[148:149], v[194:195], v[148:149]
	v_pk_mul_f32 v[150:151], v[196:197], v[150:151]
	v_pk_add_f32 v[152:153], v[152:153], 1.0 op_sel_hi:[1,0]
	v_pk_add_f32 v[154:155], v[154:155], 1.0 op_sel_hi:[1,0]
	v_pk_mul_f32 v[152:153], v[198:199], v[152:153]
	v_pk_mul_f32 v[154:155], v[200:201], v[154:155]
	v_pk_add_f32 v[156:157], v[156:157], 1.0 op_sel_hi:[1,0]
	v_pk_add_f32 v[158:159], v[158:159], 1.0 op_sel_hi:[1,0]
	v_pk_mul_f32 v[156:157], v[202:203], v[156:157]
	v_pk_mul_f32 v[158:159], v[204:205], v[158:159]
	v_pk_add_f32 v[160:161], v[160:161], 1.0 op_sel_hi:[1,0]
	v_pk_add_f32 v[162:163], v[162:163], 1.0 op_sel_hi:[1,0]
	v_pk_mul_f32 v[160:161], v[206:207], v[160:161]
	v_pk_mul_f32 v[162:163], v[208:209], v[162:163]
	s_add_u32 s72, s60, 0x10000
	s_addc_u32 s73, s61, 0
	global_load_dwordx4 v[194:197], v211, s[72:73] offset:0
	global_load_dwordx4 v[198:201], v211, s[72:73] offset:64
	global_load_dwordx4 v[202:205], v211, s[72:73] offset:512
	global_load_dwordx4 v[206:209], v211, s[72:73] offset:576
	v_mov_b32_e32 v216, 0
	v_mov_b32_e32 v217, 0
	v_mov_b32_e32 v218, 0
	v_mov_b32_e32 v219, 0
	v_mov_b32_e32 v228, 0
	v_mov_b32_e32 v229, 0
	v_mov_b32_e32 v234, 0
	v_mov_b32_e32 v235, 0
	s_waitcnt vmcnt(4)
	s_mov_b32 s74, s62
	s_mov_b32 s75, s63
	s_mov_b32 s76, s88
	s_mov_b32 s77, s89
	v_pk_fma_f32 v[164:165], v[144:145], v[60:61], v[164:165]
	v_pk_fma_f32 v[166:167], v[146:147], v[62:63], v[166:167]
	v_pk_fma_f32 v[168:169], v[140:141], v[64:65], v[168:169]
	v_pk_fma_f32 v[170:171], v[142:143], v[66:67], v[170:171]
	global_store_dwordx4 v211, v[164:167], s[74:75] offset:0
	global_store_dwordx4 v211, v[168:171], s[74:75] offset:64
	v_fmac_f32_e32 v216, v164, v164
	v_fmac_f32_e32 v216, v165, v165
	v_fmac_f32_e32 v216, v166, v166
	v_fmac_f32_e32 v216, v167, v167
	v_pk_mul_f32 v[144:145], v[148:149], v[164:165]
	v_pk_mul_f32 v[146:147], v[150:151], v[166:167]
	v_fmac_f32_e32 v216, v168, v168
	v_fmac_f32_e32 v216, v169, v169
	v_fmac_f32_e32 v216, v170, v170
	v_fmac_f32_e32 v216, v171, v171
	v_pk_mul_f32 v[140:141], v[152:153], v[168:169]
	v_pk_mul_f32 v[142:143], v[154:155], v[170:171]
	v_cvt_pk_bf16_f32 v144, v144, v145
	v_cvt_pk_bf16_f32 v145, v146, v147
	v_cvt_pk_bf16_f32 v146, v140, v141
	v_cvt_pk_bf16_f32 v147, v142, v143
	s_nop 1
	v_permlane16_swap_b32 v144, v146
	v_permlane16_swap_b32 v145, v147
	global_store_dwordx4 v212, v[144:147], s[76:77] offset:0
	v_pk_fma_f32 v[172:173], v[136:137], v[68:69], v[172:173]
	v_pk_fma_f32 v[174:175], v[138:139], v[70:71], v[174:175]
	v_pk_fma_f32 v[176:177], v[132:133], v[72:73], v[176:177]
	v_pk_fma_f32 v[178:179], v[134:135], v[74:75], v[178:179]
	global_store_dwordx4 v211, v[172:175], s[74:75] offset:512
	global_store_dwordx4 v211, v[176:179], s[74:75] offset:576
	v_fmac_f32_e32 v216, v172, v172
	v_fmac_f32_e32 v216, v173, v173
	v_fmac_f32_e32 v216, v174, v174
	v_fmac_f32_e32 v216, v175, v175
	v_pk_mul_f32 v[136:137], v[156:157], v[172:173]
	v_pk_mul_f32 v[138:139], v[158:159], v[174:175]
	v_fmac_f32_e32 v216, v176, v176
	v_fmac_f32_e32 v216, v177, v177
	v_fmac_f32_e32 v216, v178, v178
	v_fmac_f32_e32 v216, v179, v179
	v_pk_mul_f32 v[132:133], v[160:161], v[176:177]
	v_pk_mul_f32 v[134:135], v[162:163], v[178:179]
	v_cvt_pk_bf16_f32 v136, v136, v137
	v_cvt_pk_bf16_f32 v137, v138, v139
	v_cvt_pk_bf16_f32 v138, v132, v133
	v_cvt_pk_bf16_f32 v139, v134, v135
	s_nop 1
	v_permlane16_swap_b32 v136, v138
	v_permlane16_swap_b32 v137, v139
	global_store_dwordx4 v212, v[136:139], s[76:77] offset:256
	s_add_u32 s72, s60, 0x20000
	s_addc_u32 s73, s61, 0
	global_load_dwordx4 v[164:167], v211, s[72:73] offset:0
	global_load_dwordx4 v[168:171], v211, s[72:73] offset:64
	global_load_dwordx4 v[172:175], v211, s[72:73] offset:512
	global_load_dwordx4 v[176:179], v211, s[72:73] offset:576
	s_add_u32 s72, s60, 0x30000
	s_addc_u32 s73, s61, 0
	global_load_dwordx4 v[144:147], v211, s[72:73] offset:0
	global_load_dwordx4 v[140:143], v211, s[72:73] offset:64
	global_load_dwordx4 v[136:139], v211, s[72:73] offset:512
	global_load_dwordx4 v[132:135], v211, s[72:73] offset:576
	s_waitcnt vmcnt(14)
	s_add_u32 s74, s62, 0x10000
	s_addc_u32 s75, s63, 0
	s_add_u32 s76, s88, 0x8000
	s_addc_u32 s77, s89, 0
	v_pk_fma_f32 v[194:195], v[128:129], v[60:61], v[194:195]
	v_pk_fma_f32 v[196:197], v[130:131], v[62:63], v[196:197]
	v_pk_fma_f32 v[198:199], v[124:125], v[64:65], v[198:199]
	v_pk_fma_f32 v[200:201], v[126:127], v[66:67], v[200:201]
	global_store_dwordx4 v211, v[194:197], s[74:75] offset:0
	global_store_dwordx4 v211, v[198:201], s[74:75] offset:64
	v_fmac_f32_e32 v217, v194, v194
	v_fmac_f32_e32 v217, v195, v195
	v_fmac_f32_e32 v217, v196, v196
	v_fmac_f32_e32 v217, v197, v197
	v_pk_mul_f32 v[128:129], v[148:149], v[194:195]
	v_pk_mul_f32 v[130:131], v[150:151], v[196:197]
	v_fmac_f32_e32 v217, v198, v198
	v_fmac_f32_e32 v217, v199, v199
	v_fmac_f32_e32 v217, v200, v200
	v_fmac_f32_e32 v217, v201, v201
	v_pk_mul_f32 v[124:125], v[152:153], v[198:199]
	v_pk_mul_f32 v[126:127], v[154:155], v[200:201]
	v_cvt_pk_bf16_f32 v128, v128, v129
	v_cvt_pk_bf16_f32 v129, v130, v131
	v_cvt_pk_bf16_f32 v130, v124, v125
	v_cvt_pk_bf16_f32 v131, v126, v127
	s_nop 1
	v_permlane16_swap_b32 v128, v130
	v_permlane16_swap_b32 v129, v131
	global_store_dwordx4 v212, v[128:131], s[76:77] offset:0
	v_pk_fma_f32 v[202:203], v[120:121], v[68:69], v[202:203]
	v_pk_fma_f32 v[204:205], v[122:123], v[70:71], v[204:205]
	v_pk_fma_f32 v[206:207], v[116:117], v[72:73], v[206:207]
	v_pk_fma_f32 v[208:209], v[118:119], v[74:75], v[208:209]
	global_store_dwordx4 v211, v[202:205], s[74:75] offset:512
	global_store_dwordx4 v211, v[206:209], s[74:75] offset:576
	v_fmac_f32_e32 v217, v202, v202
	v_fmac_f32_e32 v217, v203, v203
	v_fmac_f32_e32 v217, v204, v204
	v_fmac_f32_e32 v217, v205, v205
	v_pk_mul_f32 v[120:121], v[156:157], v[202:203]
	v_pk_mul_f32 v[122:123], v[158:159], v[204:205]
	v_fmac_f32_e32 v217, v206, v206
	v_fmac_f32_e32 v217, v207, v207
	v_fmac_f32_e32 v217, v208, v208
	v_fmac_f32_e32 v217, v209, v209
	v_pk_mul_f32 v[116:117], v[160:161], v[206:207]
	v_pk_mul_f32 v[118:119], v[162:163], v[208:209]
	v_cvt_pk_bf16_f32 v120, v120, v121
	v_cvt_pk_bf16_f32 v121, v122, v123
	v_cvt_pk_bf16_f32 v122, v116, v117
	v_cvt_pk_bf16_f32 v123, v118, v119
	s_nop 1
	v_permlane16_swap_b32 v120, v122
	v_permlane16_swap_b32 v121, v123
	global_store_dwordx4 v212, v[120:123], s[76:77] offset:256
	s_add_u32 s72, s60, 0x80000
	s_addc_u32 s73, s61, 0
	global_load_dwordx4 v[194:197], v211, s[72:73] offset:0
	global_load_dwordx4 v[198:201], v211, s[72:73] offset:64
	global_load_dwordx4 v[202:205], v211, s[72:73] offset:512
	global_load_dwordx4 v[206:209], v211, s[72:73] offset:576
	s_add_u32 s72, s60, 0x90000
	s_addc_u32 s73, s61, 0
	global_load_dwordx4 v[128:131], v211, s[72:73] offset:0
	global_load_dwordx4 v[124:127], v211, s[72:73] offset:64
	global_load_dwordx4 v[120:123], v211, s[72:73] offset:512
	global_load_dwordx4 v[116:119], v211, s[72:73] offset:576
	s_waitcnt vmcnt(18)
	s_add_u32 s74, s62, 0x20000
	s_addc_u32 s75, s63, 0
	s_add_u32 s76, s88, 0x10000
	s_addc_u32 s77, s89, 0
	v_pk_fma_f32 v[164:165], v[112:113], v[60:61], v[164:165]
	v_pk_fma_f32 v[166:167], v[114:115], v[62:63], v[166:167]
	v_pk_fma_f32 v[168:169], v[108:109], v[64:65], v[168:169]
	v_pk_fma_f32 v[170:171], v[110:111], v[66:67], v[170:171]
	global_store_dwordx4 v211, v[164:167], s[74:75] offset:0
	global_store_dwordx4 v211, v[168:171], s[74:75] offset:64
	v_fmac_f32_e32 v218, v164, v164
	v_fmac_f32_e32 v218, v165, v165
	v_fmac_f32_e32 v218, v166, v166
	v_fmac_f32_e32 v218, v167, v167
	v_pk_mul_f32 v[112:113], v[148:149], v[164:165]
	v_pk_mul_f32 v[114:115], v[150:151], v[166:167]
	v_fmac_f32_e32 v218, v168, v168
	v_fmac_f32_e32 v218, v169, v169
	v_fmac_f32_e32 v218, v170, v170
	v_fmac_f32_e32 v218, v171, v171
	v_pk_mul_f32 v[108:109], v[152:153], v[168:169]
	v_pk_mul_f32 v[110:111], v[154:155], v[170:171]
	v_cvt_pk_bf16_f32 v112, v112, v113
	v_cvt_pk_bf16_f32 v113, v114, v115
	v_cvt_pk_bf16_f32 v114, v108, v109
	v_cvt_pk_bf16_f32 v115, v110, v111
	s_nop 1
	v_permlane16_swap_b32 v112, v114
	v_permlane16_swap_b32 v113, v115
	global_store_dwordx4 v212, v[112:115], s[76:77] offset:0
	v_pk_fma_f32 v[172:173], v[104:105], v[68:69], v[172:173]
	v_pk_fma_f32 v[174:175], v[106:107], v[70:71], v[174:175]
	v_pk_fma_f32 v[176:177], v[100:101], v[72:73], v[176:177]
	v_pk_fma_f32 v[178:179], v[102:103], v[74:75], v[178:179]
	global_store_dwordx4 v211, v[172:175], s[74:75] offset:512
	global_store_dwordx4 v211, v[176:179], s[74:75] offset:576
	v_fmac_f32_e32 v218, v172, v172
	v_fmac_f32_e32 v218, v173, v173
	v_fmac_f32_e32 v218, v174, v174
	v_fmac_f32_e32 v218, v175, v175
	v_pk_mul_f32 v[104:105], v[156:157], v[172:173]
	v_pk_mul_f32 v[106:107], v[158:159], v[174:175]
	v_fmac_f32_e32 v218, v176, v176
	v_fmac_f32_e32 v218, v177, v177
	v_fmac_f32_e32 v218, v178, v178
	v_fmac_f32_e32 v218, v179, v179
	v_pk_mul_f32 v[100:101], v[160:161], v[176:177]
	v_pk_mul_f32 v[102:103], v[162:163], v[178:179]
	v_cvt_pk_bf16_f32 v104, v104, v105
	v_cvt_pk_bf16_f32 v105, v106, v107
	v_cvt_pk_bf16_f32 v106, v100, v101
	v_cvt_pk_bf16_f32 v107, v102, v103
	s_nop 1
	v_permlane16_swap_b32 v104, v106
	v_permlane16_swap_b32 v105, v107
	global_store_dwordx4 v212, v[104:107], s[76:77] offset:256
	s_add_u32 s72, s60, 0xa0000
	s_addc_u32 s73, s61, 0
	global_load_dwordx4 v[164:167], v211, s[72:73] offset:0
	global_load_dwordx4 v[168:171], v211, s[72:73] offset:64
	global_load_dwordx4 v[172:175], v211, s[72:73] offset:512
	global_load_dwordx4 v[176:179], v211, s[72:73] offset:576
	s_add_u32 s72, s60, 0xb0000
	s_addc_u32 s73, s61, 0
	global_load_dwordx4 v[112:115], v211, s[72:73] offset:0
	global_load_dwordx4 v[108:111], v211, s[72:73] offset:64
	global_load_dwordx4 v[104:107], v211, s[72:73] offset:512
	global_load_dwordx4 v[100:103], v211, s[72:73] offset:576
	s_waitcnt vmcnt(28)
	s_add_u32 s74, s62, 0x30000
	s_addc_u32 s75, s63, 0
	s_add_u32 s76, s88, 0x18000
	s_addc_u32 s77, s89, 0
	v_pk_fma_f32 v[144:145], v[92:93], v[60:61], v[144:145]
	v_pk_fma_f32 v[146:147], v[94:95], v[62:63], v[146:147]
	v_pk_fma_f32 v[140:141], v[88:89], v[64:65], v[140:141]
	v_pk_fma_f32 v[142:143], v[90:91], v[66:67], v[142:143]
	global_store_dwordx4 v211, v[144:147], s[74:75] offset:0
	global_store_dwordx4 v211, v[140:143], s[74:75] offset:64
	v_fmac_f32_e32 v219, v144, v144
	v_fmac_f32_e32 v219, v145, v145
	v_fmac_f32_e32 v219, v146, v146
	v_fmac_f32_e32 v219, v147, v147
	v_pk_mul_f32 v[92:93], v[148:149], v[144:145]
	v_pk_mul_f32 v[94:95], v[150:151], v[146:147]
	v_fmac_f32_e32 v219, v140, v140
	v_fmac_f32_e32 v219, v141, v141
	v_fmac_f32_e32 v219, v142, v142
	v_fmac_f32_e32 v219, v143, v143
	v_pk_mul_f32 v[88:89], v[152:153], v[140:141]
	v_pk_mul_f32 v[90:91], v[154:155], v[142:143]
	v_cvt_pk_bf16_f32 v92, v92, v93
	v_cvt_pk_bf16_f32 v93, v94, v95
	v_cvt_pk_bf16_f32 v94, v88, v89
	v_cvt_pk_bf16_f32 v95, v90, v91
	s_nop 1
	v_permlane16_swap_b32 v92, v94
	v_permlane16_swap_b32 v93, v95
	global_store_dwordx4 v212, v[92:95], s[76:77] offset:0
	v_pk_fma_f32 v[136:137], v[84:85], v[68:69], v[136:137]
	v_pk_fma_f32 v[138:139], v[86:87], v[70:71], v[138:139]
	v_pk_fma_f32 v[132:133], v[80:81], v[72:73], v[132:133]
	v_pk_fma_f32 v[134:135], v[82:83], v[74:75], v[134:135]
	global_store_dwordx4 v211, v[136:139], s[74:75] offset:512
	global_store_dwordx4 v211, v[132:135], s[74:75] offset:576
	v_fmac_f32_e32 v219, v136, v136
	v_fmac_f32_e32 v219, v137, v137
	v_fmac_f32_e32 v219, v138, v138
	v_fmac_f32_e32 v219, v139, v139
	v_pk_mul_f32 v[84:85], v[156:157], v[136:137]
	v_pk_mul_f32 v[86:87], v[158:159], v[138:139]
	v_fmac_f32_e32 v219, v132, v132
	v_fmac_f32_e32 v219, v133, v133
	v_fmac_f32_e32 v219, v134, v134
	v_fmac_f32_e32 v219, v135, v135
	v_pk_mul_f32 v[80:81], v[160:161], v[132:133]
	v_pk_mul_f32 v[82:83], v[162:163], v[134:135]
	v_cvt_pk_bf16_f32 v84, v84, v85
	v_cvt_pk_bf16_f32 v85, v86, v87
	v_cvt_pk_bf16_f32 v86, v80, v81
	v_cvt_pk_bf16_f32 v87, v82, v83
	s_nop 1
	v_permlane16_swap_b32 v84, v86
	v_permlane16_swap_b32 v85, v87
	global_store_dwordx4 v212, v[84:87], s[76:77] offset:256
	s_waitcnt vmcnt(24)
	s_add_u32 s74, s62, 0x80000
	s_addc_u32 s75, s63, 0
	s_add_u32 s76, s88, 0x40000
	s_addc_u32 s77, s89, 0
	v_pk_fma_f32 v[194:195], v[76:77], v[60:61], v[194:195]
	v_pk_fma_f32 v[196:197], v[78:79], v[62:63], v[196:197]
	v_pk_fma_f32 v[198:199], v[56:57], v[64:65], v[198:199]
	v_pk_fma_f32 v[200:201], v[58:59], v[66:67], v[200:201]
	global_store_dwordx4 v211, v[194:197], s[74:75] offset:0
	global_store_dwordx4 v211, v[198:201], s[74:75] offset:64
	v_fmac_f32_e32 v228, v194, v194
	v_fmac_f32_e32 v228, v195, v195
	v_fmac_f32_e32 v228, v196, v196
	v_fmac_f32_e32 v228, v197, v197
	v_pk_mul_f32 v[76:77], v[148:149], v[194:195]
	v_pk_mul_f32 v[78:79], v[150:151], v[196:197]
	v_fmac_f32_e32 v228, v198, v198
	v_fmac_f32_e32 v228, v199, v199
	v_fmac_f32_e32 v228, v200, v200
	v_fmac_f32_e32 v228, v201, v201
	v_pk_mul_f32 v[56:57], v[152:153], v[198:199]
	v_pk_mul_f32 v[58:59], v[154:155], v[200:201]
	v_cvt_pk_bf16_f32 v76, v76, v77
	v_cvt_pk_bf16_f32 v77, v78, v79
	v_cvt_pk_bf16_f32 v78, v56, v57
	v_cvt_pk_bf16_f32 v79, v58, v59
	s_nop 1
	v_permlane16_swap_b32 v76, v78
	v_permlane16_swap_b32 v77, v79
	global_store_dwordx4 v212, v[76:79], s[76:77] offset:0
	v_pk_fma_f32 v[202:203], v[52:53], v[68:69], v[202:203]
	v_pk_fma_f32 v[204:205], v[54:55], v[70:71], v[204:205]
	v_pk_fma_f32 v[206:207], v[48:49], v[72:73], v[206:207]
	v_pk_fma_f32 v[208:209], v[50:51], v[74:75], v[208:209]
	global_store_dwordx4 v211, v[202:205], s[74:75] offset:512
	global_store_dwordx4 v211, v[206:209], s[74:75] offset:576
	v_fmac_f32_e32 v228, v202, v202
	v_fmac_f32_e32 v228, v203, v203
	v_fmac_f32_e32 v228, v204, v204
	v_fmac_f32_e32 v228, v205, v205
	v_pk_mul_f32 v[52:53], v[156:157], v[202:203]
	v_pk_mul_f32 v[54:55], v[158:159], v[204:205]
	v_fmac_f32_e32 v228, v206, v206
	v_fmac_f32_e32 v228, v207, v207
	v_fmac_f32_e32 v228, v208, v208
	v_fmac_f32_e32 v228, v209, v209
	v_pk_mul_f32 v[48:49], v[160:161], v[206:207]
	v_pk_mul_f32 v[50:51], v[162:163], v[208:209]
	v_cvt_pk_bf16_f32 v52, v52, v53
	v_cvt_pk_bf16_f32 v53, v54, v55
	v_cvt_pk_bf16_f32 v54, v48, v49
	v_cvt_pk_bf16_f32 v55, v50, v51
	s_nop 1
	v_permlane16_swap_b32 v52, v54
	v_permlane16_swap_b32 v53, v55
	global_store_dwordx4 v212, v[52:55], s[76:77] offset:256
	s_waitcnt vmcnt(26)
	s_add_u32 s74, s62, 0x90000
	s_addc_u32 s75, s63, 0
	s_add_u32 s76, s88, 0x48000
	s_addc_u32 s77, s89, 0
	v_pk_fma_f32 v[128:129], v[44:45], v[60:61], v[128:129]
	v_pk_fma_f32 v[130:131], v[46:47], v[62:63], v[130:131]
	v_pk_fma_f32 v[124:125], v[40:41], v[64:65], v[124:125]
	v_pk_fma_f32 v[126:127], v[42:43], v[66:67], v[126:127]
	global_store_dwordx4 v211, v[128:131], s[74:75] offset:0
	global_store_dwordx4 v211, v[124:127], s[74:75] offset:64
	v_fmac_f32_e32 v229, v128, v128
	v_fmac_f32_e32 v229, v129, v129
	v_fmac_f32_e32 v229, v130, v130
	v_fmac_f32_e32 v229, v131, v131
	v_pk_mul_f32 v[44:45], v[148:149], v[128:129]
	v_pk_mul_f32 v[46:47], v[150:151], v[130:131]
	v_fmac_f32_e32 v229, v124, v124
	v_fmac_f32_e32 v229, v125, v125
	v_fmac_f32_e32 v229, v126, v126
	v_fmac_f32_e32 v229, v127, v127
	v_pk_mul_f32 v[40:41], v[152:153], v[124:125]
	v_pk_mul_f32 v[42:43], v[154:155], v[126:127]
	v_cvt_pk_bf16_f32 v44, v44, v45
	v_cvt_pk_bf16_f32 v45, v46, v47
	v_cvt_pk_bf16_f32 v46, v40, v41
	v_cvt_pk_bf16_f32 v47, v42, v43
	s_nop 1
	v_permlane16_swap_b32 v44, v46
	v_permlane16_swap_b32 v45, v47
	global_store_dwordx4 v212, v[44:47], s[76:77] offset:0
	v_pk_fma_f32 v[120:121], v[36:37], v[68:69], v[120:121]
	v_pk_fma_f32 v[122:123], v[38:39], v[70:71], v[122:123]
	v_pk_fma_f32 v[116:117], v[32:33], v[72:73], v[116:117]
	v_pk_fma_f32 v[118:119], v[34:35], v[74:75], v[118:119]
	global_store_dwordx4 v211, v[120:123], s[74:75] offset:512
	global_store_dwordx4 v211, v[116:119], s[74:75] offset:576
	v_fmac_f32_e32 v229, v120, v120
	v_fmac_f32_e32 v229, v121, v121
	v_fmac_f32_e32 v229, v122, v122
	v_fmac_f32_e32 v229, v123, v123
	v_pk_mul_f32 v[36:37], v[156:157], v[120:121]
	v_pk_mul_f32 v[38:39], v[158:159], v[122:123]
	v_fmac_f32_e32 v229, v116, v116
	v_fmac_f32_e32 v229, v117, v117
	v_fmac_f32_e32 v229, v118, v118
	v_fmac_f32_e32 v229, v119, v119
	v_pk_mul_f32 v[32:33], v[160:161], v[116:117]
	v_pk_mul_f32 v[34:35], v[162:163], v[118:119]
	v_cvt_pk_bf16_f32 v36, v36, v37
	v_cvt_pk_bf16_f32 v37, v38, v39
	v_cvt_pk_bf16_f32 v38, v32, v33
	v_cvt_pk_bf16_f32 v39, v34, v35
	s_nop 1
	v_permlane16_swap_b32 v36, v38
	v_permlane16_swap_b32 v37, v39
	global_store_dwordx4 v212, v[36:39], s[76:77] offset:256
	s_waitcnt vmcnt(22)
	s_add_u32 s74, s62, 0xa0000
	s_addc_u32 s75, s63, 0
	s_add_u32 s76, s88, 0x50000
	s_addc_u32 s77, s89, 0
	v_pk_fma_f32 v[164:165], v[28:29], v[60:61], v[164:165]
	v_pk_fma_f32 v[166:167], v[30:31], v[62:63], v[166:167]
	v_pk_fma_f32 v[168:169], v[24:25], v[64:65], v[168:169]
	v_pk_fma_f32 v[170:171], v[26:27], v[66:67], v[170:171]
	global_store_dwordx4 v211, v[164:167], s[74:75] offset:0
	global_store_dwordx4 v211, v[168:171], s[74:75] offset:64
	v_fmac_f32_e32 v234, v164, v164
	v_fmac_f32_e32 v234, v165, v165
	v_fmac_f32_e32 v234, v166, v166
	v_fmac_f32_e32 v234, v167, v167
	v_pk_mul_f32 v[28:29], v[148:149], v[164:165]
	v_pk_mul_f32 v[30:31], v[150:151], v[166:167]
	v_fmac_f32_e32 v234, v168, v168
	v_fmac_f32_e32 v234, v169, v169
	v_fmac_f32_e32 v234, v170, v170
	v_fmac_f32_e32 v234, v171, v171
	v_pk_mul_f32 v[24:25], v[152:153], v[168:169]
	v_pk_mul_f32 v[26:27], v[154:155], v[170:171]
	v_cvt_pk_bf16_f32 v28, v28, v29
	v_cvt_pk_bf16_f32 v29, v30, v31
	v_cvt_pk_bf16_f32 v30, v24, v25
	v_cvt_pk_bf16_f32 v31, v26, v27
	s_nop 1
	v_permlane16_swap_b32 v28, v30
	v_permlane16_swap_b32 v29, v31
	global_store_dwordx4 v212, v[28:31], s[76:77] offset:0
	v_pk_fma_f32 v[172:173], v[20:21], v[68:69], v[172:173]
	v_pk_fma_f32 v[174:175], v[22:23], v[70:71], v[174:175]
	v_pk_fma_f32 v[176:177], v[16:17], v[72:73], v[176:177]
	v_pk_fma_f32 v[178:179], v[18:19], v[74:75], v[178:179]
	global_store_dwordx4 v211, v[172:175], s[74:75] offset:512
	global_store_dwordx4 v211, v[176:179], s[74:75] offset:576
	v_fmac_f32_e32 v234, v172, v172
	v_fmac_f32_e32 v234, v173, v173
	v_fmac_f32_e32 v234, v174, v174
	v_fmac_f32_e32 v234, v175, v175
	v_pk_mul_f32 v[20:21], v[156:157], v[172:173]
	v_pk_mul_f32 v[22:23], v[158:159], v[174:175]
	v_fmac_f32_e32 v234, v176, v176
	v_fmac_f32_e32 v234, v177, v177
	v_fmac_f32_e32 v234, v178, v178
	v_fmac_f32_e32 v234, v179, v179
	v_pk_mul_f32 v[16:17], v[160:161], v[176:177]
	v_pk_mul_f32 v[18:19], v[162:163], v[178:179]
	v_cvt_pk_bf16_f32 v20, v20, v21
	v_cvt_pk_bf16_f32 v21, v22, v23
	v_cvt_pk_bf16_f32 v22, v16, v17
	v_cvt_pk_bf16_f32 v23, v18, v19
	s_nop 1
	v_permlane16_swap_b32 v20, v22
	v_permlane16_swap_b32 v21, v23
	global_store_dwordx4 v212, v[20:23], s[76:77] offset:256
	s_waitcnt vmcnt(24)
	s_add_u32 s74, s62, 0xb0000
	s_addc_u32 s75, s63, 0
	s_add_u32 s76, s88, 0x58000
	s_addc_u32 s77, s89, 0
	v_pk_fma_f32 v[112:113], v[12:13], v[60:61], v[112:113]
	v_pk_fma_f32 v[114:115], v[14:15], v[62:63], v[114:115]
	v_pk_fma_f32 v[108:109], v[8:9], v[64:65], v[108:109]
	v_pk_fma_f32 v[110:111], v[10:11], v[66:67], v[110:111]
	global_store_dwordx4 v211, v[112:115], s[74:75] offset:0
	global_store_dwordx4 v211, v[108:111], s[74:75] offset:64
	v_fmac_f32_e32 v235, v112, v112
	v_fmac_f32_e32 v235, v113, v113
	v_fmac_f32_e32 v235, v114, v114
	v_fmac_f32_e32 v235, v115, v115
	v_pk_mul_f32 v[12:13], v[148:149], v[112:113]
	v_pk_mul_f32 v[14:15], v[150:151], v[114:115]
	v_fmac_f32_e32 v235, v108, v108
	v_fmac_f32_e32 v235, v109, v109
	v_fmac_f32_e32 v235, v110, v110
	v_fmac_f32_e32 v235, v111, v111
	v_pk_mul_f32 v[8:9], v[152:153], v[108:109]
	v_pk_mul_f32 v[10:11], v[154:155], v[110:111]
	v_cvt_pk_bf16_f32 v12, v12, v13
	v_cvt_pk_bf16_f32 v13, v14, v15
	v_cvt_pk_bf16_f32 v14, v8, v9
	v_cvt_pk_bf16_f32 v15, v10, v11
	s_nop 1
	v_permlane16_swap_b32 v12, v14
	v_permlane16_swap_b32 v13, v15
	global_store_dwordx4 v212, v[12:15], s[76:77] offset:0
	v_pk_fma_f32 v[104:105], v[4:5], v[68:69], v[104:105]
	v_pk_fma_f32 v[106:107], v[6:7], v[70:71], v[106:107]
	v_pk_fma_f32 v[100:101], v[0:1], v[72:73], v[100:101]
	v_pk_fma_f32 v[102:103], v[2:3], v[74:75], v[102:103]
	global_store_dwordx4 v211, v[104:107], s[74:75] offset:512
	global_store_dwordx4 v211, v[100:103], s[74:75] offset:576
	v_fmac_f32_e32 v235, v104, v104
	v_fmac_f32_e32 v235, v105, v105
	v_fmac_f32_e32 v235, v106, v106
	v_fmac_f32_e32 v235, v107, v107
	v_pk_mul_f32 v[4:5], v[156:157], v[104:105]
	v_pk_mul_f32 v[6:7], v[158:159], v[106:107]
	v_fmac_f32_e32 v235, v100, v100
	v_fmac_f32_e32 v235, v101, v101
	v_fmac_f32_e32 v235, v102, v102
	v_fmac_f32_e32 v235, v103, v103
	v_pk_mul_f32 v[0:1], v[160:161], v[100:101]
	v_pk_mul_f32 v[2:3], v[162:163], v[102:103]
	v_cvt_pk_bf16_f32 v4, v4, v5
	v_cvt_pk_bf16_f32 v5, v6, v7
	v_cvt_pk_bf16_f32 v6, v0, v1
	v_cvt_pk_bf16_f32 v7, v2, v3
	s_nop 1
	v_permlane16_swap_b32 v4, v6
	v_permlane16_swap_b32 v5, v7
	global_store_dwordx4 v212, v[4:7], s[76:77] offset:256
	ds_bpermute_b32 v164, v214, v216
	ds_bpermute_b32 v165, v214, v217
	ds_bpermute_b32 v166, v214, v218
	ds_bpermute_b32 v167, v214, v219
	ds_bpermute_b32 v168, v214, v228
	ds_bpermute_b32 v169, v214, v229
	ds_bpermute_b32 v170, v214, v234
	ds_bpermute_b32 v171, v214, v235
	s_waitcnt lgkmcnt(0)
	v_add_f32_e32 v216, v216, v164
	v_add_f32_e32 v217, v217, v165
	v_add_f32_e32 v218, v218, v166
	v_add_f32_e32 v219, v219, v167
	v_add_f32_e32 v228, v228, v168
	v_add_f32_e32 v229, v229, v169
	v_add_f32_e32 v234, v234, v170
	v_add_f32_e32 v235, v235, v171
	ds_bpermute_b32 v164, v215, v216
	ds_bpermute_b32 v165, v215, v217
	ds_bpermute_b32 v166, v215, v218
	ds_bpermute_b32 v167, v215, v219
	ds_bpermute_b32 v168, v215, v228
	ds_bpermute_b32 v169, v215, v229
	ds_bpermute_b32 v170, v215, v234
	ds_bpermute_b32 v171, v215, v235
	s_waitcnt lgkmcnt(0)
	v_add_f32_e32 v216, v216, v164
	v_add_f32_e32 v217, v217, v165
	v_add_f32_e32 v218, v218, v166
	v_add_f32_e32 v219, v219, v167
	v_add_f32_e32 v228, v228, v168
	v_add_f32_e32 v229, v229, v169
	v_add_f32_e32 v234, v234, v170
	v_add_f32_e32 v235, v235, v171
	s_and_saveexec_b64 s[44:45], s[40:41]
	s_cbranch_execz .Lresid_noatom
	global_atomic_add_f32 v213, v216, s[6:7] offset:0
	global_atomic_add_f32 v213, v217, s[6:7] offset:64
	global_atomic_add_f32 v213, v218, s[6:7] offset:128
	global_atomic_add_f32 v213, v219, s[6:7] offset:192
	global_atomic_add_f32 v213, v228, s[6:7] offset:512
	global_atomic_add_f32 v213, v229, s[6:7] offset:576
	global_atomic_add_f32 v213, v234, s[6:7] offset:640
	global_atomic_add_f32 v213, v235, s[6:7] offset:704

.Lresid_nonorm:
	v_readlane_b32 s62, v252, 7
	v_readlane_b32 s63, v252, 8
	s_lshr_b32 s20, s56, 4
	s_mul_i32 s20, s20, 0x6000
	s_add_u32 s44, s66, s20
	s_addc_u32 s45, s12, 0
	s_add_u32 s46, s13, s20
	s_addc_u32 s47, s26, 0
	s_mov_b32 s60, s38
	s_mov_b32 s61, s95
	v_lshl_or_b32 v236, s57, 8, v246
	v_lshl_add_u32 v237, s56, 8, v244
	v_lshlrev_b32_e32 v210, 2, v236
	v_lshl_add_u32 v211, v237, 12, v210
	v_and_b32_e32 v212, 4, v246
	v_mul_u32_u24_e32 v212, 6, v212
	v_lshl_add_u32 v212, v236, 1, v212
	v_lshl_add_u32 v212, v237, 11, v212
	v_lshlrev_b32_e32 v213, 2, v237
	v_lshlrev_b32_e32 v214, 2, v231
	v_lshlrev_b32_e32 v215, 2, v232
	global_load_dwordx4 v[60:63], v210, s[44:45] offset:0
	global_load_dwordx4 v[64:67], v210, s[44:45] offset:64
	global_load_dwordx4 v[68:71], v210, s[44:45] offset:512
	global_load_dwordx4 v[72:75], v210, s[44:45] offset:576
	s_mov_b32 s72, s60
	s_mov_b32 s73, s61
	global_load_dwordx4 v[164:167], v211, s[72:73] offset:0
	global_load_dwordx4 v[168:171], v211, s[72:73] offset:64
	global_load_dwordx4 v[172:175], v211, s[72:73] offset:512
	global_load_dwordx4 v[176:179], v211, s[72:73] offset:576
	s_add_u32 s72, s60, 0x10000
	s_addc_u32 s73, s61, 0
	global_load_dwordx4 v[194:197], v211, s[72:73] offset:0
	global_load_dwordx4 v[198:201], v211, s[72:73] offset:64
	global_load_dwordx4 v[202:205], v211, s[72:73] offset:512
	global_load_dwordx4 v[206:209], v211, s[72:73] offset:576
	s_waitcnt vmcnt(4)
	s_mov_b32 s74, s62
	s_mov_b32 s75, s63
	v_pk_fma_f32 v[164:165], v[144:145], v[60:61], v[164:165]
	v_pk_fma_f32 v[166:167], v[146:147], v[62:63], v[166:167]
	v_pk_fma_f32 v[168:169], v[140:141], v[64:65], v[168:169]
	v_pk_fma_f32 v[170:171], v[142:143], v[66:67], v[170:171]
	global_store_dwordx4 v211, v[164:167], s[74:75] offset:0
	global_store_dwordx4 v211, v[168:171], s[74:75] offset:64
	v_pk_fma_f32 v[172:173], v[136:137], v[68:69], v[172:173]
	v_pk_fma_f32 v[174:175], v[138:139], v[70:71], v[174:175]
	v_pk_fma_f32 v[176:177], v[132:133], v[72:73], v[176:177]
	v_pk_fma_f32 v[178:179], v[134:135], v[74:75], v[178:179]
	global_store_dwordx4 v211, v[172:175], s[74:75] offset:512
	global_store_dwordx4 v211, v[176:179], s[74:75] offset:576
	s_add_u32 s72, s60, 0x20000
	s_addc_u32 s73, s61, 0
	global_load_dwordx4 v[164:167], v211, s[72:73] offset:0
	global_load_dwordx4 v[168:171], v211, s[72:73] offset:64
	global_load_dwordx4 v[172:175], v211, s[72:73] offset:512
	global_load_dwordx4 v[176:179], v211, s[72:73] offset:576
	s_add_u32 s72, s60, 0x30000
	s_addc_u32 s73, s61, 0
	global_load_dwordx4 v[144:147], v211, s[72:73] offset:0
	global_load_dwordx4 v[140:143], v211, s[72:73] offset:64
	global_load_dwordx4 v[136:139], v211, s[72:73] offset:512
	global_load_dwordx4 v[132:135], v211, s[72:73] offset:576
	s_waitcnt vmcnt(12)
	s_add_u32 s74, s62, 0x10000
	s_addc_u32 s75, s63, 0
	v_pk_fma_f32 v[194:195], v[128:129], v[60:61], v[194:195]
	v_pk_fma_f32 v[196:197], v[130:131], v[62:63], v[196:197]
	v_pk_fma_f32 v[198:199], v[124:125], v[64:65], v[198:199]
	v_pk_fma_f32 v[200:201], v[126:127], v[66:67], v[200:201]
	global_store_dwordx4 v211, v[194:197], s[74:75] offset:0
	global_store_dwordx4 v211, v[198:201], s[74:75] offset:64
	v_pk_fma_f32 v[202:203], v[120:121], v[68:69], v[202:203]
	v_pk_fma_f32 v[204:205], v[122:123], v[70:71], v[204:205]
	v_pk_fma_f32 v[206:207], v[116:117], v[72:73], v[206:207]
	v_pk_fma_f32 v[208:209], v[118:119], v[74:75], v[208:209]
	global_store_dwordx4 v211, v[202:205], s[74:75] offset:512
	global_store_dwordx4 v211, v[206:209], s[74:75] offset:576
	s_add_u32 s72, s60, 0x80000
	s_addc_u32 s73, s61, 0
	global_load_dwordx4 v[194:197], v211, s[72:73] offset:0
	global_load_dwordx4 v[198:201], v211, s[72:73] offset:64
	global_load_dwordx4 v[202:205], v211, s[72:73] offset:512
	global_load_dwordx4 v[206:209], v211, s[72:73] offset:576
	s_add_u32 s72, s60, 0x90000
	s_addc_u32 s73, s61, 0
	global_load_dwordx4 v[128:131], v211, s[72:73] offset:0
	global_load_dwordx4 v[124:127], v211, s[72:73] offset:64
	global_load_dwordx4 v[120:123], v211, s[72:73] offset:512
	global_load_dwordx4 v[116:119], v211, s[72:73] offset:576
	s_waitcnt vmcnt(16)
	s_add_u32 s74, s62, 0x20000
	s_addc_u32 s75, s63, 0
	v_pk_fma_f32 v[164:165], v[112:113], v[60:61], v[164:165]
	v_pk_fma_f32 v[166:167], v[114:115], v[62:63], v[166:167]
	v_pk_fma_f32 v[168:169], v[108:109], v[64:65], v[168:169]
	v_pk_fma_f32 v[170:171], v[110:111], v[66:67], v[170:171]
	global_store_dwordx4 v211, v[164:167], s[74:75] offset:0
	global_store_dwordx4 v211, v[168:171], s[74:75] offset:64
	v_pk_fma_f32 v[172:173], v[104:105], v[68:69], v[172:173]
	v_pk_fma_f32 v[174:175], v[106:107], v[70:71], v[174:175]
	v_pk_fma_f32 v[176:177], v[100:101], v[72:73], v[176:177]
	v_pk_fma_f32 v[178:179], v[102:103], v[74:75], v[178:179]
	global_store_dwordx4 v211, v[172:175], s[74:75] offset:512
	global_store_dwordx4 v211, v[176:179], s[74:75] offset:576
	s_add_u32 s72, s60, 0xa0000
	s_addc_u32 s73, s61, 0
	global_load_dwordx4 v[164:167], v211, s[72:73] offset:0
	global_load_dwordx4 v[168:171], v211, s[72:73] offset:64
	global_load_dwordx4 v[172:175], v211, s[72:73] offset:512
	global_load_dwordx4 v[176:179], v211, s[72:73] offset:576
	s_add_u32 s72, s60, 0xb0000
	s_addc_u32 s73, s61, 0
	global_load_dwordx4 v[112:115], v211, s[72:73] offset:0
	global_load_dwordx4 v[108:111], v211, s[72:73] offset:64
	global_load_dwordx4 v[104:107], v211, s[72:73] offset:512
	global_load_dwordx4 v[100:103], v211, s[72:73] offset:576
	s_waitcnt vmcnt(24)
	s_add_u32 s74, s62, 0x30000
	s_addc_u32 s75, s63, 0
	v_pk_fma_f32 v[144:145], v[92:93], v[60:61], v[144:145]
	v_pk_fma_f32 v[146:147], v[94:95], v[62:63], v[146:147]
	v_pk_fma_f32 v[140:141], v[88:89], v[64:65], v[140:141]
	v_pk_fma_f32 v[142:143], v[90:91], v[66:67], v[142:143]
	global_store_dwordx4 v211, v[144:147], s[74:75] offset:0
	global_store_dwordx4 v211, v[140:143], s[74:75] offset:64
	v_pk_fma_f32 v[136:137], v[84:85], v[68:69], v[136:137]
	v_pk_fma_f32 v[138:139], v[86:87], v[70:71], v[138:139]
	v_pk_fma_f32 v[132:133], v[80:81], v[72:73], v[132:133]
	v_pk_fma_f32 v[134:135], v[82:83], v[74:75], v[134:135]
	global_store_dwordx4 v211, v[136:139], s[74:75] offset:512
	global_store_dwordx4 v211, v[132:135], s[74:75] offset:576
	s_waitcnt vmcnt(20)
	s_add_u32 s74, s62, 0x80000
	s_addc_u32 s75, s63, 0
	v_pk_fma_f32 v[194:195], v[76:77], v[60:61], v[194:195]
	v_pk_fma_f32 v[196:197], v[78:79], v[62:63], v[196:197]
	v_pk_fma_f32 v[198:199], v[56:57], v[64:65], v[198:199]
	v_pk_fma_f32 v[200:201], v[58:59], v[66:67], v[200:201]
	global_store_dwordx4 v211, v[194:197], s[74:75] offset:0
	global_store_dwordx4 v211, v[198:201], s[74:75] offset:64
	v_pk_fma_f32 v[202:203], v[52:53], v[68:69], v[202:203]
	v_pk_fma_f32 v[204:205], v[54:55], v[70:71], v[204:205]
	v_pk_fma_f32 v[206:207], v[48:49], v[72:73], v[206:207]
	v_pk_fma_f32 v[208:209], v[50:51], v[74:75], v[208:209]
	global_store_dwordx4 v211, v[202:205], s[74:75] offset:512
	global_store_dwordx4 v211, v[206:209], s[74:75] offset:576
	s_waitcnt vmcnt(20)
	s_add_u32 s74, s62, 0x90000
	s_addc_u32 s75, s63, 0
	v_pk_fma_f32 v[128:129], v[44:45], v[60:61], v[128:129]
	v_pk_fma_f32 v[130:131], v[46:47], v[62:63], v[130:131]
	v_pk_fma_f32 v[124:125], v[40:41], v[64:65], v[124:125]
	v_pk_fma_f32 v[126:127], v[42:43], v[66:67], v[126:127]
	global_store_dwordx4 v211, v[128:131], s[74:75] offset:0
	global_store_dwordx4 v211, v[124:127], s[74:75] offset:64
	v_pk_fma_f32 v[120:121], v[36:37], v[68:69], v[120:121]
	v_pk_fma_f32 v[122:123], v[38:39], v[70:71], v[122:123]
	v_pk_fma_f32 v[116:117], v[32:33], v[72:73], v[116:117]
	v_pk_fma_f32 v[118:119], v[34:35], v[74:75], v[118:119]
	global_store_dwordx4 v211, v[120:123], s[74:75] offset:512
	global_store_dwordx4 v211, v[116:119], s[74:75] offset:576
	s_waitcnt vmcnt(16)
	s_add_u32 s74, s62, 0xa0000
	s_addc_u32 s75, s63, 0
	v_pk_fma_f32 v[164:165], v[28:29], v[60:61], v[164:165]
	v_pk_fma_f32 v[166:167], v[30:31], v[62:63], v[166:167]
	v_pk_fma_f32 v[168:169], v[24:25], v[64:65], v[168:169]
	v_pk_fma_f32 v[170:171], v[26:27], v[66:67], v[170:171]
	global_store_dwordx4 v211, v[164:167], s[74:75] offset:0
	global_store_dwordx4 v211, v[168:171], s[74:75] offset:64
	v_pk_fma_f32 v[172:173], v[20:21], v[68:69], v[172:173]
	v_pk_fma_f32 v[174:175], v[22:23], v[70:71], v[174:175]
	v_pk_fma_f32 v[176:177], v[16:17], v[72:73], v[176:177]
	v_pk_fma_f32 v[178:179], v[18:19], v[74:75], v[178:179]
	global_store_dwordx4 v211, v[172:175], s[74:75] offset:512
	global_store_dwordx4 v211, v[176:179], s[74:75] offset:576
	s_waitcnt vmcnt(16)
	s_add_u32 s74, s62, 0xb0000
	s_addc_u32 s75, s63, 0
	v_pk_fma_f32 v[112:113], v[12:13], v[60:61], v[112:113]
	v_pk_fma_f32 v[114:115], v[14:15], v[62:63], v[114:115]
	v_pk_fma_f32 v[108:109], v[8:9], v[64:65], v[108:109]
	v_pk_fma_f32 v[110:111], v[10:11], v[66:67], v[110:111]
	global_store_dwordx4 v211, v[112:115], s[74:75] offset:0
	global_store_dwordx4 v211, v[108:111], s[74:75] offset:64
	v_pk_fma_f32 v[104:105], v[4:5], v[68:69], v[104:105]
	v_pk_fma_f32 v[106:107], v[6:7], v[70:71], v[106:107]
	v_pk_fma_f32 v[100:101], v[0:1], v[72:73], v[100:101]
	v_pk_fma_f32 v[102:103], v[2:3], v[74:75], v[102:103]
	global_store_dwordx4 v211, v[104:107], s[74:75] offset:512
	global_store_dwordx4 v211, v[100:103], s[74:75] offset:576
	s_branch .Lresid_done
